# barrier routine: pointers stashed in v255 lanes (no scalar loads), LDS writes start as each load lands (counted vmcnt), uniform 34 loads
# baseline (speedup 1.0000x reference)
; #define GAS __attribute__((address_space(1)))
; #define LAS __attribute__((address_space(3)))
; #define LDS_WAIT() asm volatile("s_waitcnt lgkmcnt(0)" ::: "memory")
; __device__ __forceinline__ unsigned pk2(float lo, float hi) { return f2bf(lo) | (f2bf(hi) << 16); }
; __device__ __forceinline__ void transpose_item(const float* W, const float* g  , int K, int N, bf16* WT, LAS float* scr, int kb, int nb, int lane) {
;     const int k0 = 64 * kb, n0 = 32 * nb;
; #pragma unroll 8
;     for (int i = 0; i < 32; ++i) { const int kk = 2 * i + (lane >> 5); const float gv = g ? g[k0 + kk] : 1.f; scr[kk * 33 + (lane & 31)] = W[(size_t)(k0 + kk) * N + n0 + (lane & 31)] * gv; }
;     LDS_WAIT(); asm volatile("" ::: "memory");
;     const int c = lane & 7;
; #pragma unroll
;     for (int j = 0; j < 4; ++j) { const int n = (lane >> 3) + 8 * j; const LAS float* s = scr + (8 * c) * 33 + n;
;         v4u o; o.x = pk2(s[0 * 33], s[1 * 33]); o.y = pk2(s[2 * 33], s[3 * 33]); o.z = pk2(s[4 * 33], s[5 * 33]); o.w = pk2(s[6 * 33], s[7 * 33]);
;         *(GAS v4u*)(WT + (size_t)(n0 + n) * K + k0 + 8 * c) = o; }
;     LDS_WAIT(); asm volatile("" ::: "memory");
; }
; __device__ __forceinline__ void transpose_tensor(const float* W, const float* g, int gstep, int nl, int K, int N, bf16* WT, LAS float* scr, int gw, int NGW, int lane) {
;     const int nblk = N / 32, per = (K / 64) * nblk, total = nl * per;
;     for (int it = gw; it < total; it += NGW) { const int l = it / per, r = it - l * per;
;         transpose_item(W + (size_t)l * K * N, g ? g + (size_t)l * gstep : nullptr, K, N, WT + (size_t)l * K * N, scr, r / nblk, r % nblk, lane); }
.LBB0_13:
.LBB0_14:
	v_readlane_b32 s10, v252, 0
	v_readlane_b32 s11, v252, 1
	s_mov_b32 s61, 0
	v_writelane_b32 v255, s61, 6
	v_lshrrev_b32_e32 v100, 6, v0
	v_and_b32_e32 v101, 63, v0
	s_load_dwordx2 s[12:13], s[10:11], 0xd0
	s_load_dwordx2 s[70:71], s[10:11], 0xb8
	s_load_dwordx2 s[72:73], s[10:11], 0xc0
	s_load_dwordx2 s[74:75], s[10:11], 0x38
	v_readfirstlane_b32 s14, v100
	v_lshrrev_b32_e32 v102, 5, v101
	v_and_b32_e32 v103, 31, v101
	v_and_b32_e32 v105, 7, v101
	v_lshrrev_b32_e32 v106, 3, v101
	s_lshl_b32 s15, s59, 3
	s_add_i32 s15, s15, s14
	s_lshl_b32 s16, s60, 3
	s_lshl_b32 s17, s14, 14
	s_mul_i32 s69, s60, 70
	s_min_u32 s69, s69, 0x4000
	s_min_u32 s67, s69, 0x2000
	s_max_u32 s68, s69, 0x2000
	s_sub_u32 s68, s68, 0x2000
	v_mad_u32_u24 v104, v102, 33, v103
	v_lshl_add_u32 v104, v104, 2, s17
	v_mul_u32_u24_e32 v107, 0x108, v105
	v_add_u32_e32 v107, v107, v106
	v_lshl_add_u32 v107, v107, 2, s17
	v_lshlrev_b32_e32 v108, 5, v105
	v_lshlrev_b32_e32 v109, 2, v103
	v_lshlrev_b32_e32 v105, 4, v105
	s_mov_b32 s18, 0
	s_waitcnt lgkmcnt(0)
	v_writelane_b32 v255, s12, 7
	v_writelane_b32 v255, s13, 8
	v_writelane_b32 v255, s70, 9
	v_writelane_b32 v255, s71, 10
	v_writelane_b32 v255, s72, 11
	v_writelane_b32 v255, s73, 12
	v_writelane_b32 v255, s74, 13
	v_writelane_b32 v255, s75, 14

; #define LAS __attribute__((address_space(3)))
; __device__ __forceinline__ void transpose_tensor(const float* W, const float* g, int gstep, int nl, int K, int N, bf16* WT, LAS float* scr, int gw, int NGW, int lane) {
;     const int nblk = N / 32, per = (K / 64) * nblk, total = nl * per;
;     for (int it = gw; it < total; it += NGW) { const int l = it / per, r = it - l * per;
;         transpose_item(W + (size_t)l * K * N, g ? g + (size_t)l * gstep : nullptr, K, N, WT + (size_t)l * K * N, scr, r / nblk, r % nblk, lane); }
; __global__ void __launch_bounds__(NWAVES * 64, 2) fwd(Args args) {
;     ...
;         transpose_tensor(ka->in[23], ka->in[7], DM, 4, DM, DFF, WSB(WS_WUP), scr, gw, NGW, lane);
;         transpose_tensor(ka->in[24], nullptr, 0, 4, DFF, DM, WSB(WS_WDN), scr, gw, NGW, lane);
.Lwb_go:
	s_mul_i32 s83, s60, 7
	s_mul_i32 s84, s84, s83
	s_mul_i32 s83, s59, 7
	s_add_u32 s84, s84, s83
	s_add_u32 s84, s84, s94
	s_sub_u32 s84, s84, 1
	s_mul_i32 s69, s60, 70
	s_min_u32 s69, s69, 0x4000
	s_cmp_lt_u32 s84, s69
	s_cbranch_scc0 .Lwb_ret
	v_readlane_b32 s90, v255, 7
	v_readlane_b32 s91, v255, 8
	v_readlane_b32 s86, v255, 13
	v_readlane_b32 s87, v255, 14
	s_cmp_lt_u32 s84, 0x2000
	s_cbranch_scc0 .Lwb_dn
	v_readlane_b32 s88, v255, 9
	v_readlane_b32 s89, v255, 10
	s_lshr_b32 s83, s84, 8
	s_and_b32 s82, s84, 0xff
	s_mov_b32 s73, 0x8000
	s_mov_b32 s72, 0x1000
	s_mov_b32 s78, 0x200000
	s_mov_b32 s77, 0x20000
	s_mov_b32 s75, 0x11000000
	s_mov_b32 s74, 1
	s_branch .Lwb_cm
.Lwb_dn:
	v_readlane_b32 s88, v255, 11
	v_readlane_b32 s89, v255, 12
	s_sub_u32 s81, s84, 0x2000
	s_lshr_b32 s83, s81, 6
	s_and_b32 s82, s81, 63
	s_mov_b32 s73, 0x2000
	s_mov_b32 s72, 0x4000
	s_mov_b32 s78, 0x80000
	s_mov_b32 s77, 0x80000
	s_mov_b32 s75, 0x19000000
	s_mov_b32 s74, 0

; #define GAS __attribute__((address_space(1)))
; #define LAS __attribute__((address_space(3)))
; #define LDS_WAIT() asm volatile("s_waitcnt lgkmcnt(0)" ::: "memory")
; __device__ __forceinline__ unsigned pk2(float lo, float hi) { return f2bf(lo) | (f2bf(hi) << 16); }
; __device__ __forceinline__ void transpose_item(const float* W, const float* g  , int K, int N, bf16* WT, LAS float* scr, int kb, int nb, int lane) {
;     const int k0 = 64 * kb, n0 = 32 * nb;
; #pragma unroll 8
;     for (int i = 0; i < 32; ++i) { const int kk = 2 * i + (lane >> 5); const float gv = g ? g[k0 + kk] : 1.f; scr[kk * 33 + (lane & 31)] = W[(size_t)(k0 + kk) * N + n0 + (lane & 31)] * gv; }
;     LDS_WAIT(); asm volatile("" ::: "memory");
;     const int c = lane & 7;
; #pragma unroll
;     for (int j = 0; j < 4; ++j) { const int n = (lane >> 3) + 8 * j; const LAS float* s = scr + (8 * c) * 33 + n;
;         v4u o; o.x = pk2(s[0 * 33], s[1 * 33]); o.y = pk2(s[2 * 33], s[3 * 33]); o.z = pk2(s[4 * 33], s[5 * 33]); o.w = pk2(s[6 * 33], s[7 * 33]);
;         *(GAS v4u*)(WT + (size_t)(n0 + n) * K + k0 + 8 * c) = o; }
;     LDS_WAIT(); asm volatile("" ::: "memory");
; }
.Lwb_ng:
	v_mov_b32_e32 v56, 1.0
	v_mov_b32_e32 v57, 1.0
	v_mov_b32_e32 v58, 1.0
	v_mov_b32_e32 v59, 1.0
	v_mov_b32_e32 v60, 1.0
	v_mov_b32_e32 v61, 1.0
	v_mov_b32_e32 v62, 1.0
	v_mov_b32_e32 v63, 1.0
	global_load_dwordx4 v[70:73], v66, s[86:87]
	global_load_dwordx4 v[74:77], v66, s[86:87] offset:16
.Lwb_ld:
	s_waitcnt vmcnt(33)
	ds_write_b32 v67, v24
	s_waitcnt vmcnt(32)
	ds_write_b32 v67, v25 offset:264
	s_waitcnt vmcnt(31)
	ds_write_b32 v67, v26 offset:528
	s_waitcnt vmcnt(30)
	ds_write_b32 v67, v27 offset:792
	s_waitcnt vmcnt(29)
	ds_write_b32 v67, v28 offset:1056
	s_waitcnt vmcnt(28)
	ds_write_b32 v67, v29 offset:1320
	s_waitcnt vmcnt(27)
	ds_write_b32 v67, v30 offset:1584
	s_waitcnt vmcnt(26)
	ds_write_b32 v67, v31 offset:1848
	s_waitcnt vmcnt(25)
	ds_write_b32 v67, v32 offset:2112
	s_waitcnt vmcnt(24)
	ds_write_b32 v67, v33 offset:2376
	s_waitcnt vmcnt(23)
	ds_write_b32 v67, v34 offset:2640
	s_waitcnt vmcnt(22)
	ds_write_b32 v67, v35 offset:2904
	s_waitcnt vmcnt(21)
	ds_write_b32 v67, v36 offset:3168
	s_waitcnt vmcnt(20)
	ds_write_b32 v67, v37 offset:3432
	s_waitcnt vmcnt(19)
	ds_write_b32 v67, v38 offset:3696
	s_waitcnt vmcnt(18)
	ds_write_b32 v67, v39 offset:3960
	s_waitcnt vmcnt(17)
	ds_write_b32 v67, v40 offset:4224
	s_waitcnt vmcnt(16)
	ds_write_b32 v67, v41 offset:4488
	s_waitcnt vmcnt(15)
	ds_write_b32 v67, v42 offset:4752
	s_waitcnt vmcnt(14)
	ds_write_b32 v67, v43 offset:5016
	s_waitcnt vmcnt(13)
	ds_write_b32 v67, v44 offset:5280
	s_waitcnt vmcnt(12)
	ds_write_b32 v67, v45 offset:5544
	s_waitcnt vmcnt(11)
	ds_write_b32 v67, v46 offset:5808
	s_waitcnt vmcnt(10)
	ds_write_b32 v67, v47 offset:6072
	s_waitcnt vmcnt(9)
	ds_write_b32 v67, v48 offset:6336
	s_waitcnt vmcnt(8)
	ds_write_b32 v67, v49 offset:6600
	s_waitcnt vmcnt(7)
	ds_write_b32 v67, v50 offset:6864
	s_waitcnt vmcnt(6)
	ds_write_b32 v67, v51 offset:7128
	s_waitcnt vmcnt(5)
	ds_write_b32 v67, v52 offset:7392
	s_waitcnt vmcnt(4)
	ds_write_b32 v67, v53 offset:7656
	s_waitcnt vmcnt(3)
	ds_write_b32 v67, v54 offset:7920
	s_waitcnt vmcnt(2)
	ds_write_b32 v67, v55 offset:8184
	s_waitcnt vmcnt(0)
	s_waitcnt lgkmcnt(0)
	ds_read2_b32 v[24:25], v68 offset0:0 offset1:33
	ds_read2_b32 v[26:27], v68 offset0:66 offset1:99
	ds_read2_b32 v[28:29], v68 offset0:132 offset1:165
	ds_read2_b32 v[30:31], v68 offset0:198 offset1:231
	ds_read2_b32 v[32:33], v68 offset0:8 offset1:41
	ds_read2_b32 v[34:35], v68 offset0:74 offset1:107
	ds_read2_b32 v[36:37], v68 offset0:140 offset1:173
	ds_read2_b32 v[38:39], v68 offset0:206 offset1:239
	ds_read2_b32 v[40:41], v68 offset0:16 offset1:49
	ds_read2_b32 v[42:43], v68 offset0:82 offset1:115
	ds_read2_b32 v[44:45], v68 offset0:148 offset1:181
	ds_read2_b32 v[46:47], v68 offset0:214 offset1:247
	ds_read2_b32 v[48:49], v68 offset0:24 offset1:57
	ds_read2_b32 v[50:51], v68 offset0:90 offset1:123
	ds_read2_b32 v[52:53], v68 offset0:156 offset1:189
	ds_read2_b32 v[54:55], v68 offset0:222 offset1:255
	s_waitcnt lgkmcnt(15)
	v_mul_f32_e32 v24, v56, v24
	v_mul_f32_e32 v25, v57, v25
	v_cvt_pk_bf16_f32 v24, v24, v25
	s_waitcnt lgkmcnt(14)
	v_mul_f32_e32 v26, v58, v26
	v_mul_f32_e32 v27, v59, v27
	v_cvt_pk_bf16_f32 v25, v26, v27
	s_waitcnt lgkmcnt(13)
	v_mul_f32_e32 v28, v60, v28
	v_mul_f32_e32 v29, v61, v29
	v_cvt_pk_bf16_f32 v26, v28, v29
	s_waitcnt lgkmcnt(12)
	v_mul_f32_e32 v30, v62, v30
	v_mul_f32_e32 v31, v63, v31
	v_cvt_pk_bf16_f32 v27, v30, v31
	global_store_dwordx4 v65, v[24:27], s[90:91]
	s_add_u32 s90, s90, s79
	s_addc_u32 s91, s91, 0
	s_waitcnt lgkmcnt(11)
	v_mul_f32_e32 v32, v56, v32
	v_mul_f32_e32 v33, v57, v33
	v_cvt_pk_bf16_f32 v32, v32, v33
	s_waitcnt lgkmcnt(10)
	v_mul_f32_e32 v34, v58, v34
	v_mul_f32_e32 v35, v59, v35
	v_cvt_pk_bf16_f32 v33, v34, v35
	s_waitcnt lgkmcnt(9)
	v_mul_f32_e32 v36, v60, v36
	v_mul_f32_e32 v37, v61, v37
	v_cvt_pk_bf16_f32 v34, v36, v37
	s_waitcnt lgkmcnt(8)
	v_mul_f32_e32 v38, v62, v38
	v_mul_f32_e32 v39, v63, v39
	v_cvt_pk_bf16_f32 v35, v38, v39
	global_store_dwordx4 v65, v[32:35], s[90:91]
	s_add_u32 s90, s90, s79
	s_addc_u32 s91, s91, 0
	s_waitcnt lgkmcnt(7)
	v_mul_f32_e32 v40, v56, v40
	v_mul_f32_e32 v41, v57, v41
	v_cvt_pk_bf16_f32 v40, v40, v41
	s_waitcnt lgkmcnt(6)
	v_mul_f32_e32 v42, v58, v42
	v_mul_f32_e32 v43, v59, v43
	v_cvt_pk_bf16_f32 v41, v42, v43
	s_waitcnt lgkmcnt(5)
	v_mul_f32_e32 v44, v60, v44
	v_mul_f32_e32 v45, v61, v45
	v_cvt_pk_bf16_f32 v42, v44, v45
	s_waitcnt lgkmcnt(4)
	v_mul_f32_e32 v46, v62, v46
	v_mul_f32_e32 v47, v63, v47
	v_cvt_pk_bf16_f32 v43, v46, v47
	global_store_dwordx4 v65, v[40:43], s[90:91]
	s_add_u32 s90, s90, s79
	s_addc_u32 s91, s91, 0
	s_waitcnt lgkmcnt(3)
	v_mul_f32_e32 v48, v56, v48
	v_mul_f32_e32 v49, v57, v49
	v_cvt_pk_bf16_f32 v48, v48, v49
	s_waitcnt lgkmcnt(2)
	v_mul_f32_e32 v50, v58, v50
	v_mul_f32_e32 v51, v59, v51
	v_cvt_pk_bf16_f32 v49, v50, v51
	s_waitcnt lgkmcnt(1)
	v_mul_f32_e32 v52, v60, v52
	v_mul_f32_e32 v53, v61, v53
	v_cvt_pk_bf16_f32 v50, v52, v53
	s_waitcnt lgkmcnt(0)
	v_mul_f32_e32 v54, v62, v54
	v_mul_f32_e32 v55, v63, v55
	v_cvt_pk_bf16_f32 v51, v54, v55
	global_store_dwordx4 v65, v[48:51], s[90:91]
	s_mov_b64 exec, s[70:71]
